# SEAM3: idle waves 2-7 warm L2/TLB with input-only tables (cre, cim, wglu, dskip, bglu, sample h state) that the first P4 step reads
# baseline (speedup 1.0000x reference)
; __device__ __forceinline__ unsigned pk2(float lo, float hi) { return pg8::cvt_pk_bf16(lo, hi); }
; __device__ __forceinline__ void s5_load_consts(S5C& K, const Args& a, int g, int lane) {
;     const int fr = lane & 15, q = lane >> 4;
;     const float* ABAR = (const float*)(a.ws + WS_S5C + S5C_ABAR) + (size_t)g * 128;
;     const bf16* BBAR = (const bf16*)(a.ws + WS_S5C + S5C_BBAR) + (size_t)g * 2048;
; #pragma unroll
;     for (int j = 0; j < 4; ++j) { const f32x4 x0 = *(const f32x4*)(ABAR + 2 * (16 * j + 4 * q)), x1 = *(const f32x4*)(ABAR + 2 * (16 * j + 4 * q) + 4);
;         K.ar[j] = (f32x4){x0[0], x0[2], x1[0], x1[2]}; K.ai[j] = (f32x4){x0[1], x0[3], x1[1], x1[3]}; }
; #pragma unroll
;     for (int mt = 0; mt < 8; ++mt) K.Bf[mt] = *(const v2u*)(BBAR + (mt * 16 + fr) * 16 + 4 * q);
;     const float* cre = a.in[I_CRE] + ((size_t)g * 16 + fr) * 64; const float* cim = a.in[I_CIM] + ((size_t)g * 16 + fr) * 64;
; #pragma unroll
;     for (int j = 0; j < 4; ++j) { const f32x4 r4 = *(const f32x4*)(cre + 16 * j + 4 * q), i4 = *(const f32x4*)(cim + 16 * j + 4 * q); K.Cf[j] = pack8(r4, -i4); }
;     const float* wg = a.in[I_WGLU] + (size_t)g * 512;
;     { f32x4 v, gt;
; #pragma unroll
;       for (int e = 0; e < 4; ++e) { v[e] = wg[(4 * q + e) * 32 + fr]; gt[e] = wg[(4 * q + e) * 32 + 16 + fr]; }
;       K.Wv = (v2u){pk2(v[0], v[1]), pk2(v[2], v[3])}; K.Wg = (v2u){pk2(gt[0], gt[1]), pk2(gt[2], gt[3])}; }
;     K.dsk = *(const f32x4*)(a.in[I_DSKIP] + g * 16 + 4 * q);
;     K.bv = *(const f32x4*)(a.in[I_BGLU] + g * 32 + 4 * q); K.bg = *(const f32x4*)(a.in[I_BGLU] + g * 32 + 16 + 4 * q);
; __device__ __forceinline__ void s5_sample_task(const Args& a, int rb, int g, int lane) {
;     const bf16* PROJ = (const bf16*)(a.ws + WS_PROJ); bf16* Y = (bf16*)(a.ws + WS_Y);
;     const int n = lane & 15, q = lane >> 4, i = 16 * rb + n; const size_t row = (size_t)NBATCH * SEQ + i;
;     S5C K; s5_load_consts(K, a, g, lane);
;     f32x4 hre[4], him[4];
;     const float* sre = a.in[I_SRE] + ((size_t)i * NG + g) * PST; const float* sim = a.in[I_SIM] + ((size_t)i * NG + g) * PST;
; #pragma unroll
;     for (int j = 0; j < 4; ++j) { hre[j] = *(const f32x4*)(sre + 16 * j + 4 * q); him[j] = *(const f32x4*)(sim + 16 * j + 4 * q); }
.LBB0_944:
	s_or_b64 exec, exec, s[10:11]
	s_waitcnt vmcnt(0)
	s_branch .LBB0_945
.Lpf3:
	s_mov_b64 exec, s[4:5]
	v_readlane_b32 s36, v249, 0
	s_lshl_b32 s36, s36, 1
	s_and_b32 s37, s36, 63
	s_lshr_b32 s38, s36, 6
	v_lshlrev_b32_e32 v254, 7, v162
	s_mov_b32 s41, 0
	s_cmp_eq_u32 s82, 1
	s_cbranch_scc1 .LBB0_945
.Lpf3_w2:
	s_cmp_lg_u32 s82, 2
	s_cbranch_scc1 .Lpf3_w3
	v_readlane_b32 s42, v249, 7
	v_readlane_b32 s43, v249, 8
	s_lshl_b32 s40, s37, 12
	s_add_u32 s40, s42, s40
	s_addc_u32 s41, s43, 0
	s_branch .Lpf3_ld
.Lpf3_w3:
	s_cmp_lg_u32 s82, 3
	s_cbranch_scc1 .Lpf3_w4
	v_readlane_b32 s42, v249, 9
	v_readlane_b32 s43, v249, 10
	s_lshl_b32 s40, s37, 12
	s_add_u32 s40, s42, s40
	s_addc_u32 s41, s43, 0
	s_branch .Lpf3_ld
.Lpf3_w4:
	s_cmp_lg_u32 s82, 4
	s_cbranch_scc1 .Lpf3_w5
	v_readlane_b32 s42, v249, 13
	v_readlane_b32 s43, v249, 14
	s_lshl_b32 s40, s37, 11
	s_add_u32 s40, s42, s40
	s_addc_u32 s41, s43, 0
	v_and_b32_e32 v254, 31, v162
	v_lshlrev_b32_e32 v254, 7, v254
	s_branch .Lpf3_ld
.Lpf3_w5:
	s_cmp_lg_u32 s82, 5
	s_cbranch_scc1 .Lpf3_w6
	v_readlane_b32 s42, v249, 11
	v_readlane_b32 s43, v249, 12
	s_lshl_b32 s40, s37, 6
	s_add_u32 s40, s42, s40
	s_addc_u32 s41, s43, 0
	v_mov_b32_e32 v254, 0
	s_nop 4
	global_load_dword v255, v254, s[40:41]
	v_readlane_b32 s42, v249, 15
	v_readlane_b32 s43, v249, 16
	s_lshl_b32 s40, s37, 7
	s_add_u32 s40, s42, s40
	s_addc_u32 s41, s43, 0
	v_and_b32_e32 v254, 1, v162
	v_lshlrev_b32_e32 v254, 7, v254
	s_branch .Lpf3_ld
.Lpf3_w6:
	v_readlane_b32 s42, v249, 29
	v_readlane_b32 s43, v249, 30
	s_cmp_lg_u32 s82, 6
	s_cbranch_scc0 .Lpf3_st
	v_readlane_b32 s42, v249, 31
	v_readlane_b32 s43, v249, 32
.Lpf3_st:
	s_lshl_b32 s40, s38, 18
	s_lshl_b32 s39, s37, 8
	s_add_u32 s40, s40, s39
	s_add_u32 s40, s42, s40
	s_addc_u32 s41, s43, 0
	v_lshrrev_b32_e32 v254, 2, v162
	v_lshlrev_b32_e32 v254, 14, v254
	v_and_b32_e32 v255, 3, v162
	v_lshl_or_b32 v254, v255, 7, v254
.Lpf3_ld:
	s_nop 4
	global_load_dword v255, v254, s[40:41]
